# GEMM K-loops: hand-off overlap with 4 trailing MFMAs at s_setprio 2
# baseline (speedup 1.0000x reference)
.Lk367_body:
	v_add_u32_e32 v154, s53, v144
	v_add_u32_e32 v170, s90, v144
	ds_read_b128 v[140:143], v154
	ds_read_b128 v[146:149], v154 offset:1024
	ds_read_b128 v[150:153], v154 offset:2048
	ds_read_b128 v[154:157], v154 offset:3072
	ds_read_b128 v[158:161], v170
	ds_read_b128 v[162:165], v170 offset:1024
	ds_read_b128 v[166:169], v170 offset:2048
	ds_read_b128 v[170:173], v170 offset:3072
	s_add_u32 s96, s4, 0xfff00000
	s_addc_u32 s97, s5, -1
	s_mov_b32 m0, s51
	s_nop 0
	global_load_lds_dwordx4 v128, s[96:97]
	s_mov_b32 m0, s52
	s_nop 0
	global_load_lds_dwordx4 v132, s[96:97]
	s_add_i32 m0, s49, 0xc000
	ds_read_b128 v[188:191], v145
	ds_read_b128 v[192:195], v145 offset:1024
	ds_read_b128 v[196:199], v145 offset:2048
	ds_read_b128 v[200:203], v145 offset:3072
	ds_read_b128 v[204:207], v145 offset:4096
	ds_read_b128 v[208:211], v145 offset:5120
	ds_read_b128 v[212:215], v145 offset:6144
	ds_read_b128 v[216:219], v145 offset:7168
	global_load_lds_dwordx4 v136, s[4:5]
	s_add_i32 m0, s49, 0xe000
	s_nop 0
	global_load_lds_dwordx4 v138, s[4:5]
	s_waitcnt vmcnt(8)
	s_waitcnt lgkmcnt(0)
	s_barrier
	s_setprio 1
	s_waitcnt lgkmcnt(0)
	v_mfma_f32_16x16x32_bf16 v[124:127], v[140:143], v[188:191], v[124:127]
	v_mfma_f32_16x16x32_bf16 v[120:123], v[150:153], v[188:191], v[120:123]
	v_mfma_f32_16x16x32_bf16 v[108:111], v[140:143], v[196:199], v[108:111]
	v_mfma_f32_16x16x32_bf16 v[104:107], v[150:153], v[196:199], v[104:107]
	v_mfma_f32_16x16x32_bf16 v[92:95], v[140:143], v[204:207], v[92:95]
	v_mfma_f32_16x16x32_bf16 v[88:91], v[150:153], v[204:207], v[88:91]
	v_mfma_f32_16x16x32_bf16 v[76:79], v[140:143], v[212:215], v[76:79]
	v_mfma_f32_16x16x32_bf16 v[72:75], v[150:153], v[212:215], v[72:75]
	v_mfma_f32_16x16x32_bf16 v[124:127], v[146:149], v[192:195], v[124:127]
	v_mfma_f32_16x16x32_bf16 v[120:123], v[154:157], v[192:195], v[120:123]
	v_mfma_f32_16x16x32_bf16 v[108:111], v[146:149], v[200:203], v[108:111]
	v_mfma_f32_16x16x32_bf16 v[104:107], v[154:157], v[200:203], v[104:107]
	v_mfma_f32_16x16x32_bf16 v[92:95], v[146:149], v[208:211], v[92:95]
	v_mfma_f32_16x16x32_bf16 v[88:91], v[154:157], v[208:211], v[88:91]
	v_mfma_f32_16x16x32_bf16 v[76:79], v[146:149], v[216:219], v[76:79]
	v_mfma_f32_16x16x32_bf16 v[72:75], v[154:157], v[216:219], v[72:75]
	s_setprio 0
	s_setprio 1
	v_mfma_f32_16x16x32_bf16 v[116:119], v[158:161], v[188:191], v[116:119]
	v_mfma_f32_16x16x32_bf16 v[112:115], v[166:169], v[188:191], v[112:115]
	v_mfma_f32_16x16x32_bf16 v[100:103], v[158:161], v[196:199], v[100:103]
	v_mfma_f32_16x16x32_bf16 v[96:99], v[166:169], v[196:199], v[96:99]
	v_mfma_f32_16x16x32_bf16 v[84:87], v[158:161], v[204:207], v[84:87]
	v_mfma_f32_16x16x32_bf16 v[80:83], v[166:169], v[204:207], v[80:83]
	v_mfma_f32_16x16x32_bf16 v[68:71], v[158:161], v[212:215], v[68:71]
	v_mfma_f32_16x16x32_bf16 v[64:67], v[166:169], v[212:215], v[64:67]
	v_mfma_f32_16x16x32_bf16 v[116:119], v[162:165], v[192:195], v[116:119]
	v_mfma_f32_16x16x32_bf16 v[112:115], v[170:173], v[192:195], v[112:115]
	v_mfma_f32_16x16x32_bf16 v[100:103], v[162:165], v[200:203], v[100:103]
	v_mfma_f32_16x16x32_bf16 v[96:99], v[170:173], v[200:203], v[96:99]
	s_setprio 2
	s_barrier
	v_mfma_f32_16x16x32_bf16 v[84:87], v[162:165], v[208:211], v[84:87]
	v_mfma_f32_16x16x32_bf16 v[80:83], v[170:173], v[208:211], v[80:83]
	v_mfma_f32_16x16x32_bf16 v[68:71], v[162:165], v[216:219], v[68:71]
	v_mfma_f32_16x16x32_bf16 v[64:67], v[170:173], v[216:219], v[64:67]
	s_setprio 0
	s_add_i32 s53, s53, s43
	s_add_u32 s38, s6, 0x80
	s_addc_u32 s39, s7, 0
	s_mov_b32 m0, s53
	ds_read_b128 v[188:191], v145 offset:16384
	ds_read_b128 v[192:195], v145 offset:17408
	ds_read_b128 v[196:199], v145 offset:18432
	ds_read_b128 v[200:203], v145 offset:19456
	ds_read_b128 v[204:207], v145 offset:20480
	ds_read_b128 v[208:211], v145 offset:21504
	ds_read_b128 v[212:215], v145 offset:22528
	ds_read_b128 v[216:219], v145 offset:23552
	global_load_lds_dwordx4 v130, s[6:7]
	s_add_i32 m0, s53, 0x2000
	s_add_u32 s80, s6, 0x100000
	s_addc_u32 s81, s7, 0
	s_add_i32 s53, s90, s43
	global_load_lds_dwordx4 v134, s[6:7]
	s_mov_b32 m0, s53
	s_nop 0
	global_load_lds_dwordx4 v130, s[80:81]
	s_add_i32 m0, s53, 0x2000
	s_nop 0
	global_load_lds_dwordx4 v134, s[80:81]
	s_waitcnt vmcnt(6)
	s_waitcnt lgkmcnt(0)
	s_barrier
	s_setprio 1
	s_waitcnt lgkmcnt(0)
	v_mfma_f32_16x16x32_bf16 v[60:63], v[140:143], v[188:191], v[60:63]
	v_mfma_f32_16x16x32_bf16 v[56:59], v[150:153], v[188:191], v[56:59]
	v_mfma_f32_16x16x32_bf16 v[44:47], v[140:143], v[196:199], v[44:47]
	v_mfma_f32_16x16x32_bf16 v[40:43], v[150:153], v[196:199], v[40:43]
	v_mfma_f32_16x16x32_bf16 v[28:31], v[140:143], v[204:207], v[28:31]
	v_mfma_f32_16x16x32_bf16 v[24:27], v[150:153], v[204:207], v[24:27]
	v_mfma_f32_16x16x32_bf16 v[12:15], v[140:143], v[212:215], v[12:15]
	v_mfma_f32_16x16x32_bf16 v[8:11], v[150:153], v[212:215], v[8:11]
	v_mfma_f32_16x16x32_bf16 v[60:63], v[146:149], v[192:195], v[60:63]
	v_mfma_f32_16x16x32_bf16 v[56:59], v[154:157], v[192:195], v[56:59]
	v_mfma_f32_16x16x32_bf16 v[44:47], v[146:149], v[200:203], v[44:47]
	v_mfma_f32_16x16x32_bf16 v[40:43], v[154:157], v[200:203], v[40:43]
	v_mfma_f32_16x16x32_bf16 v[28:31], v[146:149], v[208:211], v[28:31]
	v_mfma_f32_16x16x32_bf16 v[24:27], v[154:157], v[208:211], v[24:27]
	v_mfma_f32_16x16x32_bf16 v[12:15], v[146:149], v[216:219], v[12:15]
	v_mfma_f32_16x16x32_bf16 v[8:11], v[154:157], v[216:219], v[8:11]
	s_setprio 0
	s_setprio 1
	v_mfma_f32_16x16x32_bf16 v[52:55], v[158:161], v[188:191], v[52:55]
	v_mfma_f32_16x16x32_bf16 v[48:51], v[166:169], v[188:191], v[48:51]
	v_mfma_f32_16x16x32_bf16 v[36:39], v[158:161], v[196:199], v[36:39]
	v_mfma_f32_16x16x32_bf16 v[32:35], v[166:169], v[196:199], v[32:35]
	v_mfma_f32_16x16x32_bf16 v[20:23], v[158:161], v[204:207], v[20:23]
	v_mfma_f32_16x16x32_bf16 v[16:19], v[166:169], v[204:207], v[16:19]
	v_mfma_f32_16x16x32_bf16 v[4:7], v[158:161], v[212:215], v[4:7]
	v_mfma_f32_16x16x32_bf16 v[0:3], v[166:169], v[212:215], v[0:3]
	v_mfma_f32_16x16x32_bf16 v[52:55], v[162:165], v[192:195], v[52:55]
	v_mfma_f32_16x16x32_bf16 v[48:51], v[170:173], v[192:195], v[48:51]
	v_mfma_f32_16x16x32_bf16 v[36:39], v[162:165], v[200:203], v[36:39]
	v_mfma_f32_16x16x32_bf16 v[32:35], v[170:173], v[200:203], v[32:35]
	s_setprio 2
	s_barrier
	v_mfma_f32_16x16x32_bf16 v[20:23], v[162:165], v[208:211], v[20:23]
	v_mfma_f32_16x16x32_bf16 v[16:19], v[170:173], v[208:211], v[16:19]
	v_mfma_f32_16x16x32_bf16 v[4:7], v[162:165], v[216:219], v[4:7]
	v_mfma_f32_16x16x32_bf16 v[0:3], v[170:173], v[216:219], v[0:3]
	s_setprio 0
	s_add_i32 s53, 0, 0x18000
	s_add_i32 s80, 0, 0x1c000
	v_add_u32_e32 v154, s53, v144
	v_add_u32_e32 v170, s80, v144
	ds_read_b128 v[140:143], v154
	ds_read_b128 v[146:149], v154 offset:1024
	ds_read_b128 v[150:153], v154 offset:2048
	ds_read_b128 v[154:157], v154 offset:3072
	ds_read_b128 v[158:161], v170
	ds_read_b128 v[162:165], v170 offset:1024
	ds_read_b128 v[166:169], v170 offset:2048
	ds_read_b128 v[170:173], v170 offset:3072
	s_mov_b32 m0, s49
	s_nop 0
	global_load_lds_dwordx4 v128, s[30:31]
	s_mov_b32 m0, s15
	s_nop 0
	global_load_lds_dwordx4 v132, s[30:31]
	s_add_u32 s30, s30, 0x100000
	s_addc_u32 s31, s31, 0
	s_mov_b32 m0, s36
	ds_read_b128 v[188:191], v145 offset:32768
	ds_read_b128 v[192:195], v145 offset:33792
	ds_read_b128 v[196:199], v145 offset:34816
	ds_read_b128 v[200:203], v145 offset:35840
	ds_read_b128 v[204:207], v145 offset:36864
	ds_read_b128 v[208:211], v145 offset:37888
	ds_read_b128 v[212:215], v145 offset:38912
	ds_read_b128 v[216:219], v145 offset:39936
	global_load_lds_dwordx4 v128, s[30:31]
	s_mov_b32 m0, s50
	s_nop 0
	global_load_lds_dwordx4 v132, s[30:31]
	s_waitcnt vmcnt(8)
	s_waitcnt lgkmcnt(0)
	s_barrier
	s_setprio 1
	s_waitcnt lgkmcnt(0)
	v_mfma_f32_16x16x32_bf16 v[124:127], v[140:143], v[188:191], v[124:127]
	v_mfma_f32_16x16x32_bf16 v[120:123], v[150:153], v[188:191], v[120:123]
	v_mfma_f32_16x16x32_bf16 v[108:111], v[140:143], v[196:199], v[108:111]
	v_mfma_f32_16x16x32_bf16 v[104:107], v[150:153], v[196:199], v[104:107]
	v_mfma_f32_16x16x32_bf16 v[92:95], v[140:143], v[204:207], v[92:95]
	v_mfma_f32_16x16x32_bf16 v[88:91], v[150:153], v[204:207], v[88:91]
	v_mfma_f32_16x16x32_bf16 v[76:79], v[140:143], v[212:215], v[76:79]
	v_mfma_f32_16x16x32_bf16 v[72:75], v[150:153], v[212:215], v[72:75]
	v_mfma_f32_16x16x32_bf16 v[124:127], v[146:149], v[192:195], v[124:127]
	v_mfma_f32_16x16x32_bf16 v[120:123], v[154:157], v[192:195], v[120:123]
	v_mfma_f32_16x16x32_bf16 v[108:111], v[146:149], v[200:203], v[108:111]
	v_mfma_f32_16x16x32_bf16 v[104:107], v[154:157], v[200:203], v[104:107]
	v_mfma_f32_16x16x32_bf16 v[92:95], v[146:149], v[208:211], v[92:95]
	v_mfma_f32_16x16x32_bf16 v[88:91], v[154:157], v[208:211], v[88:91]
	v_mfma_f32_16x16x32_bf16 v[76:79], v[146:149], v[216:219], v[76:79]
	v_mfma_f32_16x16x32_bf16 v[72:75], v[154:157], v[216:219], v[72:75]
	s_setprio 0
	s_setprio 1
	v_mfma_f32_16x16x32_bf16 v[116:119], v[158:161], v[188:191], v[116:119]
	v_mfma_f32_16x16x32_bf16 v[112:115], v[166:169], v[188:191], v[112:115]
	v_mfma_f32_16x16x32_bf16 v[100:103], v[158:161], v[196:199], v[100:103]
	v_mfma_f32_16x16x32_bf16 v[96:99], v[166:169], v[196:199], v[96:99]
	v_mfma_f32_16x16x32_bf16 v[84:87], v[158:161], v[204:207], v[84:87]
	v_mfma_f32_16x16x32_bf16 v[80:83], v[166:169], v[204:207], v[80:83]
	v_mfma_f32_16x16x32_bf16 v[68:71], v[158:161], v[212:215], v[68:71]
	v_mfma_f32_16x16x32_bf16 v[64:67], v[166:169], v[212:215], v[64:67]
	v_mfma_f32_16x16x32_bf16 v[116:119], v[162:165], v[192:195], v[116:119]
	v_mfma_f32_16x16x32_bf16 v[112:115], v[170:173], v[192:195], v[112:115]
	v_mfma_f32_16x16x32_bf16 v[100:103], v[162:165], v[200:203], v[100:103]
	v_mfma_f32_16x16x32_bf16 v[96:99], v[170:173], v[200:203], v[96:99]
	s_setprio 2
	s_barrier
	v_mfma_f32_16x16x32_bf16 v[84:87], v[162:165], v[208:211], v[84:87]
	v_mfma_f32_16x16x32_bf16 v[80:83], v[170:173], v[208:211], v[80:83]
	v_mfma_f32_16x16x32_bf16 v[68:71], v[162:165], v[216:219], v[68:71]
	v_mfma_f32_16x16x32_bf16 v[64:67], v[170:173], v[216:219], v[64:67]
	s_setprio 0
	s_add_i32 s30, s53, s43
	s_mov_b32 m0, s30
	ds_read_b128 v[188:191], v145 offset:49152
	ds_read_b128 v[192:195], v145 offset:50176
	ds_read_b128 v[196:199], v145 offset:51200
	ds_read_b128 v[200:203], v145 offset:52224
	ds_read_b128 v[204:207], v145 offset:53248
	ds_read_b128 v[208:211], v145 offset:54272
	ds_read_b128 v[212:215], v145 offset:55296
	ds_read_b128 v[216:219], v145 offset:56320
	global_load_lds_dwordx4 v130, s[38:39]
	s_add_i32 m0, s30, 0x2000
	s_add_u32 s6, s6, 0x100080
	s_addc_u32 s7, s7, 0
	s_add_i32 s30, s80, s43
	global_load_lds_dwordx4 v134, s[38:39]
	s_mov_b32 m0, s30
	s_nop 0
	global_load_lds_dwordx4 v130, s[6:7]
	s_add_i32 m0, s30, 0x2000
	s_nop 0
	global_load_lds_dwordx4 v134, s[6:7]
	s_waitcnt vmcnt(6)
	s_waitcnt lgkmcnt(0)
	s_barrier
	s_setprio 1
	s_waitcnt lgkmcnt(0)
	v_mfma_f32_16x16x32_bf16 v[60:63], v[140:143], v[188:191], v[60:63]
	v_mfma_f32_16x16x32_bf16 v[56:59], v[150:153], v[188:191], v[56:59]
	v_mfma_f32_16x16x32_bf16 v[44:47], v[140:143], v[196:199], v[44:47]
	s_add_i32 s79, s79, 2
	v_mfma_f32_16x16x32_bf16 v[40:43], v[150:153], v[196:199], v[40:43]
	v_mfma_f32_16x16x32_bf16 v[28:31], v[140:143], v[204:207], v[28:31]
	v_mfma_f32_16x16x32_bf16 v[24:27], v[150:153], v[204:207], v[24:27]
	s_add_u32 s4, s4, 0x100
	s_addc_u32 s5, s5, 0
	v_mfma_f32_16x16x32_bf16 v[12:15], v[140:143], v[212:215], v[12:15]
	v_mfma_f32_16x16x32_bf16 v[8:11], v[150:153], v[212:215], v[8:11]
	v_mfma_f32_16x16x32_bf16 v[60:63], v[146:149], v[192:195], v[60:63]
	s_add_u32 s55, s55, 0x100
	s_addc_u32 s78, s78, 0
	v_mfma_f32_16x16x32_bf16 v[56:59], v[154:157], v[192:195], v[56:59]
	v_mfma_f32_16x16x32_bf16 v[44:47], v[146:149], v[200:203], v[44:47]
	v_mfma_f32_16x16x32_bf16 v[40:43], v[154:157], v[200:203], v[40:43]
	s_add_u32 s6, s4, 0xfff00080
	s_addc_u32 s7, s5, -1
	v_mfma_f32_16x16x32_bf16 v[28:31], v[146:149], v[208:211], v[28:31]
	v_mfma_f32_16x16x32_bf16 v[24:27], v[154:157], v[208:211], v[24:27]
	v_mfma_f32_16x16x32_bf16 v[12:15], v[146:149], v[216:219], v[12:15]
	s_add_i32 s53, 0, 0x10000
	v_mfma_f32_16x16x32_bf16 v[8:11], v[154:157], v[216:219], v[8:11]
	s_setprio 0
	s_setprio 1
	v_mfma_f32_16x16x32_bf16 v[52:55], v[158:161], v[188:191], v[52:55]
	v_mfma_f32_16x16x32_bf16 v[48:51], v[166:169], v[188:191], v[48:51]
	s_cmp_eq_u32 s79, 60
	s_cselect_b32 s31, s27, s7
	s_cselect_b32 s30, s26, s6
	s_cselect_b32 s7, s29, s78
	s_cselect_b32 s6, s28, s55
	v_mfma_f32_16x16x32_bf16 v[36:39], v[158:161], v[196:199], v[36:39]
	v_mfma_f32_16x16x32_bf16 v[32:35], v[166:169], v[196:199], v[32:35]
	v_mfma_f32_16x16x32_bf16 v[20:23], v[158:161], v[204:207], v[20:23]
	s_add_i32 s90, 0, 0x14000
	v_mfma_f32_16x16x32_bf16 v[16:19], v[166:169], v[204:207], v[16:19]
	v_mfma_f32_16x16x32_bf16 v[4:7], v[158:161], v[212:215], v[4:7]
	v_mfma_f32_16x16x32_bf16 v[0:3], v[166:169], v[212:215], v[0:3]
	s_cmp_gt_u32 s79, 61
	v_mfma_f32_16x16x32_bf16 v[52:55], v[162:165], v[192:195], v[52:55]
	v_mfma_f32_16x16x32_bf16 v[48:51], v[170:173], v[192:195], v[48:51]
	v_mfma_f32_16x16x32_bf16 v[36:39], v[162:165], v[200:203], v[36:39]
	v_mfma_f32_16x16x32_bf16 v[32:35], v[170:173], v[200:203], v[32:35]
	s_setprio 2
	s_barrier
	v_mfma_f32_16x16x32_bf16 v[20:23], v[162:165], v[208:211], v[20:23]
	v_mfma_f32_16x16x32_bf16 v[16:19], v[170:173], v[208:211], v[16:19]
	v_mfma_f32_16x16x32_bf16 v[4:7], v[162:165], v[216:219], v[4:7]
	v_mfma_f32_16x16x32_bf16 v[0:3], v[170:173], v[216:219], v[0:3]
	s_setprio 0
	s_cbranch_scc0 .Lk367_body
	s_and_b64 vcc, exec, s[24:25]
	s_cbranch_vccz .LBB0_370
	s_barrier

.LBB0_687:
	s_add_u32 s26, s24, 0xffe00080
	s_addc_u32 s27, s25, -1
	s_add_i32 s53, 0, 0x10000
	s_cmp_eq_u32 s79, 60
	s_cselect_b32 s29, s7, s27
	s_cselect_b32 s28, s6, s26
	s_cselect_b32 s27, s19, s78
	s_cselect_b32 s26, s18, s57
	s_add_i32 s85, 0, 0x14000
	v_add_u32_e32 v152, s53, v142
	v_add_u32_e32 v168, s85, v142
	ds_read_b128 v[138:141], v152
	ds_read_b128 v[144:147], v152 offset:1024
	ds_read_b128 v[148:151], v152 offset:2048
	ds_read_b128 v[152:155], v152 offset:3072
	ds_read_b128 v[156:159], v168
	ds_read_b128 v[160:163], v168 offset:1024
	ds_read_b128 v[164:167], v168 offset:2048
	ds_read_b128 v[168:171], v168 offset:3072
	s_add_u32 s98, s24, 0xffe00000
	s_addc_u32 s99, s25, -1
	s_mov_b32 m0, s44
	s_nop 0
	global_load_lds_dwordx4 v132, s[98:99]
	s_mov_b32 m0, s48
	s_nop 0
	global_load_lds_dwordx4 v130, s[98:99]
	s_add_i32 m0, s31, 0xc000
	ds_read_b128 v[172:175], v143
	ds_read_b128 v[188:191], v143 offset:1024
	ds_read_b128 v[192:195], v143 offset:2048
	ds_read_b128 v[196:199], v143 offset:3072
	ds_read_b128 v[200:203], v143 offset:4096
	ds_read_b128 v[204:207], v143 offset:5120
	ds_read_b128 v[208:211], v143 offset:6144
	ds_read_b128 v[212:215], v143 offset:7168
	global_load_lds_dwordx4 v134, s[24:25]
	s_add_i32 m0, s31, 0xe000
	s_nop 0
	global_load_lds_dwordx4 v136, s[24:25]
	s_waitcnt vmcnt(8)
	s_waitcnt lgkmcnt(0)
	s_barrier
	s_setprio 1
	s_waitcnt lgkmcnt(0)
	v_mfma_f32_16x16x32_bf16 v[124:127], v[138:141], v[172:175], v[124:127]
	v_mfma_f32_16x16x32_bf16 v[120:123], v[148:151], v[172:175], v[120:123]
	v_mfma_f32_16x16x32_bf16 v[108:111], v[138:141], v[192:195], v[108:111]
	v_mfma_f32_16x16x32_bf16 v[104:107], v[148:151], v[192:195], v[104:107]
	v_mfma_f32_16x16x32_bf16 v[92:95], v[138:141], v[200:203], v[92:95]
	v_mfma_f32_16x16x32_bf16 v[88:91], v[148:151], v[200:203], v[88:91]
	v_mfma_f32_16x16x32_bf16 v[76:79], v[138:141], v[208:211], v[76:79]
	v_mfma_f32_16x16x32_bf16 v[72:75], v[148:151], v[208:211], v[72:75]
	v_mfma_f32_16x16x32_bf16 v[124:127], v[144:147], v[188:191], v[124:127]
	v_mfma_f32_16x16x32_bf16 v[120:123], v[152:155], v[188:191], v[120:123]
	v_mfma_f32_16x16x32_bf16 v[108:111], v[144:147], v[196:199], v[108:111]
	v_mfma_f32_16x16x32_bf16 v[104:107], v[152:155], v[196:199], v[104:107]
	v_mfma_f32_16x16x32_bf16 v[92:95], v[144:147], v[204:207], v[92:95]
	v_mfma_f32_16x16x32_bf16 v[88:91], v[152:155], v[204:207], v[88:91]
	v_mfma_f32_16x16x32_bf16 v[76:79], v[144:147], v[212:215], v[76:79]
	v_mfma_f32_16x16x32_bf16 v[72:75], v[152:155], v[212:215], v[72:75]
	s_setprio 0
	s_setprio 1
	v_mfma_f32_16x16x32_bf16 v[116:119], v[156:159], v[172:175], v[116:119]
	v_mfma_f32_16x16x32_bf16 v[112:115], v[164:167], v[172:175], v[112:115]
	v_mfma_f32_16x16x32_bf16 v[100:103], v[156:159], v[192:195], v[100:103]
	v_mfma_f32_16x16x32_bf16 v[96:99], v[164:167], v[192:195], v[96:99]
	v_mfma_f32_16x16x32_bf16 v[84:87], v[156:159], v[200:203], v[84:87]
	v_mfma_f32_16x16x32_bf16 v[80:83], v[164:167], v[200:203], v[80:83]
	v_mfma_f32_16x16x32_bf16 v[68:71], v[156:159], v[208:211], v[68:71]
	v_mfma_f32_16x16x32_bf16 v[64:67], v[164:167], v[208:211], v[64:67]
	v_mfma_f32_16x16x32_bf16 v[116:119], v[160:163], v[188:191], v[116:119]
	v_mfma_f32_16x16x32_bf16 v[112:115], v[168:171], v[188:191], v[112:115]
	v_mfma_f32_16x16x32_bf16 v[100:103], v[160:163], v[196:199], v[100:103]
	v_mfma_f32_16x16x32_bf16 v[96:99], v[168:171], v[196:199], v[96:99]
	s_setprio 2
	s_barrier
	v_mfma_f32_16x16x32_bf16 v[84:87], v[160:163], v[204:207], v[84:87]
	v_mfma_f32_16x16x32_bf16 v[80:83], v[168:171], v[204:207], v[80:83]
	v_mfma_f32_16x16x32_bf16 v[68:71], v[160:163], v[212:215], v[68:71]
	v_mfma_f32_16x16x32_bf16 v[64:67], v[168:171], v[212:215], v[64:67]
	s_setprio 0
	s_add_i32 s53, s53, s30
	s_add_u32 s90, s26, 0x80
	s_addc_u32 s91, s27, 0
	s_mov_b32 m0, s53
	ds_read_b128 v[172:175], v143 offset:16384
	ds_read_b128 v[188:191], v143 offset:17408
	ds_read_b128 v[192:195], v143 offset:18432
	ds_read_b128 v[196:199], v143 offset:19456
	ds_read_b128 v[200:203], v143 offset:20480
	ds_read_b128 v[204:207], v143 offset:21504
	ds_read_b128 v[208:211], v143 offset:22528
	ds_read_b128 v[212:215], v143 offset:23552
	global_load_lds_dwordx4 v176, s[26:27]
	s_add_i32 m0, s53, 0x2000
	s_add_u32 s80, s26, 0x100000
	s_addc_u32 s81, s27, 0
	s_add_i32 s53, s85, s30
	global_load_lds_dwordx4 v128, s[26:27]
	s_mov_b32 m0, s53
	s_nop 0
	global_load_lds_dwordx4 v176, s[80:81]
	s_add_i32 m0, s53, 0x2000
	s_nop 0
	global_load_lds_dwordx4 v128, s[80:81]
	s_waitcnt vmcnt(6)
	s_waitcnt lgkmcnt(0)
	s_barrier
	s_setprio 1
	s_waitcnt lgkmcnt(0)
	v_mfma_f32_16x16x32_bf16 v[60:63], v[138:141], v[172:175], v[60:63]
	v_mfma_f32_16x16x32_bf16 v[56:59], v[148:151], v[172:175], v[56:59]
	v_mfma_f32_16x16x32_bf16 v[44:47], v[138:141], v[192:195], v[44:47]
	v_mfma_f32_16x16x32_bf16 v[40:43], v[148:151], v[192:195], v[40:43]
	v_mfma_f32_16x16x32_bf16 v[28:31], v[138:141], v[200:203], v[28:31]
	v_mfma_f32_16x16x32_bf16 v[24:27], v[148:151], v[200:203], v[24:27]
	v_mfma_f32_16x16x32_bf16 v[12:15], v[138:141], v[208:211], v[12:15]
	v_mfma_f32_16x16x32_bf16 v[8:11], v[148:151], v[208:211], v[8:11]
	v_mfma_f32_16x16x32_bf16 v[60:63], v[144:147], v[188:191], v[60:63]
	v_mfma_f32_16x16x32_bf16 v[56:59], v[152:155], v[188:191], v[56:59]
	v_mfma_f32_16x16x32_bf16 v[44:47], v[144:147], v[196:199], v[44:47]
	v_mfma_f32_16x16x32_bf16 v[40:43], v[152:155], v[196:199], v[40:43]
	v_mfma_f32_16x16x32_bf16 v[28:31], v[144:147], v[204:207], v[28:31]
	v_mfma_f32_16x16x32_bf16 v[24:27], v[152:155], v[204:207], v[24:27]
	v_mfma_f32_16x16x32_bf16 v[12:15], v[144:147], v[212:215], v[12:15]
	v_mfma_f32_16x16x32_bf16 v[8:11], v[152:155], v[212:215], v[8:11]
	s_setprio 0
	s_setprio 1
	v_mfma_f32_16x16x32_bf16 v[52:55], v[156:159], v[172:175], v[52:55]
	v_mfma_f32_16x16x32_bf16 v[48:51], v[164:167], v[172:175], v[48:51]
	v_mfma_f32_16x16x32_bf16 v[36:39], v[156:159], v[192:195], v[36:39]
	v_mfma_f32_16x16x32_bf16 v[32:35], v[164:167], v[192:195], v[32:35]
	v_mfma_f32_16x16x32_bf16 v[20:23], v[156:159], v[200:203], v[20:23]
	v_mfma_f32_16x16x32_bf16 v[16:19], v[164:167], v[200:203], v[16:19]
	v_mfma_f32_16x16x32_bf16 v[4:7], v[156:159], v[208:211], v[4:7]
	v_mfma_f32_16x16x32_bf16 v[0:3], v[164:167], v[208:211], v[0:3]
	v_mfma_f32_16x16x32_bf16 v[52:55], v[160:163], v[188:191], v[52:55]
	v_mfma_f32_16x16x32_bf16 v[48:51], v[168:171], v[188:191], v[48:51]
	v_mfma_f32_16x16x32_bf16 v[36:39], v[160:163], v[196:199], v[36:39]
	v_mfma_f32_16x16x32_bf16 v[32:35], v[168:171], v[196:199], v[32:35]
	s_setprio 2
	s_barrier
	v_mfma_f32_16x16x32_bf16 v[20:23], v[160:163], v[204:207], v[20:23]
	v_mfma_f32_16x16x32_bf16 v[16:19], v[168:171], v[204:207], v[16:19]
	v_mfma_f32_16x16x32_bf16 v[4:7], v[160:163], v[212:215], v[4:7]
	v_mfma_f32_16x16x32_bf16 v[0:3], v[168:171], v[212:215], v[0:3]
	s_setprio 0
	s_add_i32 s53, 0, 0x18000
	s_add_i32 s80, 0, 0x1c000
	v_add_u32_e32 v152, s53, v142
	v_add_u32_e32 v168, s80, v142
	ds_read_b128 v[138:141], v152
	ds_read_b128 v[144:147], v152 offset:1024
	ds_read_b128 v[148:151], v152 offset:2048
	ds_read_b128 v[152:155], v152 offset:3072
	ds_read_b128 v[156:159], v168
	ds_read_b128 v[160:163], v168 offset:1024
	ds_read_b128 v[164:167], v168 offset:2048
	ds_read_b128 v[168:171], v168 offset:3072
	s_mov_b32 m0, s31
	s_nop 0
	global_load_lds_dwordx4 v132, s[28:29]
	s_mov_b32 m0, s34
	s_nop 0
	global_load_lds_dwordx4 v130, s[28:29]
	s_add_u32 s28, s28, 0x200000
	s_addc_u32 s29, s29, 0
	s_mov_b32 m0, s35
	ds_read_b128 v[172:175], v143 offset:32768
	ds_read_b128 v[188:191], v143 offset:33792
	ds_read_b128 v[192:195], v143 offset:34816
	ds_read_b128 v[196:199], v143 offset:35840
	ds_read_b128 v[200:203], v143 offset:36864
	ds_read_b128 v[204:207], v143 offset:37888
	ds_read_b128 v[208:211], v143 offset:38912
	ds_read_b128 v[212:215], v143 offset:39936
	global_load_lds_dwordx4 v132, s[28:29]
	s_mov_b32 m0, s36
	s_nop 0
	global_load_lds_dwordx4 v130, s[28:29]
	s_waitcnt vmcnt(8)
	s_waitcnt lgkmcnt(0)
	s_barrier
	s_setprio 1
	s_waitcnt lgkmcnt(0)
	v_mfma_f32_16x16x32_bf16 v[124:127], v[138:141], v[172:175], v[124:127]
	v_mfma_f32_16x16x32_bf16 v[120:123], v[148:151], v[172:175], v[120:123]
	v_mfma_f32_16x16x32_bf16 v[108:111], v[138:141], v[192:195], v[108:111]
	v_mfma_f32_16x16x32_bf16 v[104:107], v[148:151], v[192:195], v[104:107]
	v_mfma_f32_16x16x32_bf16 v[92:95], v[138:141], v[200:203], v[92:95]
	v_mfma_f32_16x16x32_bf16 v[88:91], v[148:151], v[200:203], v[88:91]
	v_mfma_f32_16x16x32_bf16 v[76:79], v[138:141], v[208:211], v[76:79]
	v_mfma_f32_16x16x32_bf16 v[72:75], v[148:151], v[208:211], v[72:75]
	v_mfma_f32_16x16x32_bf16 v[124:127], v[144:147], v[188:191], v[124:127]
	v_mfma_f32_16x16x32_bf16 v[120:123], v[152:155], v[188:191], v[120:123]
	v_mfma_f32_16x16x32_bf16 v[108:111], v[144:147], v[196:199], v[108:111]
	v_mfma_f32_16x16x32_bf16 v[104:107], v[152:155], v[196:199], v[104:107]
	v_mfma_f32_16x16x32_bf16 v[92:95], v[144:147], v[204:207], v[92:95]
	v_mfma_f32_16x16x32_bf16 v[88:91], v[152:155], v[204:207], v[88:91]
	v_mfma_f32_16x16x32_bf16 v[76:79], v[144:147], v[212:215], v[76:79]
	v_mfma_f32_16x16x32_bf16 v[72:75], v[152:155], v[212:215], v[72:75]
	s_setprio 0
	s_setprio 1
	v_mfma_f32_16x16x32_bf16 v[116:119], v[156:159], v[172:175], v[116:119]
	v_mfma_f32_16x16x32_bf16 v[112:115], v[164:167], v[172:175], v[112:115]
	v_mfma_f32_16x16x32_bf16 v[100:103], v[156:159], v[192:195], v[100:103]
	v_mfma_f32_16x16x32_bf16 v[96:99], v[164:167], v[192:195], v[96:99]
	v_mfma_f32_16x16x32_bf16 v[84:87], v[156:159], v[200:203], v[84:87]
	v_mfma_f32_16x16x32_bf16 v[80:83], v[164:167], v[200:203], v[80:83]
	v_mfma_f32_16x16x32_bf16 v[68:71], v[156:159], v[208:211], v[68:71]
	v_mfma_f32_16x16x32_bf16 v[64:67], v[164:167], v[208:211], v[64:67]
	v_mfma_f32_16x16x32_bf16 v[116:119], v[160:163], v[188:191], v[116:119]
	v_mfma_f32_16x16x32_bf16 v[112:115], v[168:171], v[188:191], v[112:115]
	v_mfma_f32_16x16x32_bf16 v[100:103], v[160:163], v[196:199], v[100:103]
	v_mfma_f32_16x16x32_bf16 v[96:99], v[168:171], v[196:199], v[96:99]
	s_setprio 2
	s_barrier
	v_mfma_f32_16x16x32_bf16 v[84:87], v[160:163], v[204:207], v[84:87]
	v_mfma_f32_16x16x32_bf16 v[80:83], v[168:171], v[204:207], v[80:83]
	v_mfma_f32_16x16x32_bf16 v[68:71], v[160:163], v[212:215], v[68:71]
	v_mfma_f32_16x16x32_bf16 v[64:67], v[168:171], v[212:215], v[64:67]
	s_setprio 0
	s_add_i32 s28, s53, s30
	s_mov_b32 m0, s28
	ds_read_b128 v[172:175], v143 offset:49152
	ds_read_b128 v[188:191], v143 offset:50176
	ds_read_b128 v[192:195], v143 offset:51200
	ds_read_b128 v[196:199], v143 offset:52224
	ds_read_b128 v[200:203], v143 offset:53248
	ds_read_b128 v[204:207], v143 offset:54272
	ds_read_b128 v[208:211], v143 offset:55296
	ds_read_b128 v[212:215], v143 offset:56320
	global_load_lds_dwordx4 v176, s[90:91]
	s_add_i32 m0, s28, 0x2000
	s_add_u32 s26, s26, 0x100080
	s_addc_u32 s27, s27, 0
	s_add_i32 s28, s80, s30
	global_load_lds_dwordx4 v128, s[90:91]
	s_mov_b32 m0, s28
	s_nop 0
	global_load_lds_dwordx4 v176, s[26:27]
	s_add_i32 m0, s28, 0x2000
	s_nop 0
	global_load_lds_dwordx4 v128, s[26:27]
	s_waitcnt vmcnt(6)
	s_waitcnt lgkmcnt(0)
	s_barrier
	s_setprio 1
	s_waitcnt lgkmcnt(0)
	v_mfma_f32_16x16x32_bf16 v[60:63], v[138:141], v[172:175], v[60:63]
	v_mfma_f32_16x16x32_bf16 v[56:59], v[148:151], v[172:175], v[56:59]
	v_mfma_f32_16x16x32_bf16 v[44:47], v[138:141], v[192:195], v[44:47]
	v_mfma_f32_16x16x32_bf16 v[40:43], v[148:151], v[192:195], v[40:43]
	v_mfma_f32_16x16x32_bf16 v[28:31], v[138:141], v[200:203], v[28:31]
	v_mfma_f32_16x16x32_bf16 v[24:27], v[148:151], v[200:203], v[24:27]
	v_mfma_f32_16x16x32_bf16 v[12:15], v[138:141], v[208:211], v[12:15]
	v_mfma_f32_16x16x32_bf16 v[8:11], v[148:151], v[208:211], v[8:11]
	v_mfma_f32_16x16x32_bf16 v[60:63], v[144:147], v[188:191], v[60:63]
	v_mfma_f32_16x16x32_bf16 v[56:59], v[152:155], v[188:191], v[56:59]
	v_mfma_f32_16x16x32_bf16 v[44:47], v[144:147], v[196:199], v[44:47]
	v_mfma_f32_16x16x32_bf16 v[40:43], v[152:155], v[196:199], v[40:43]
	v_mfma_f32_16x16x32_bf16 v[28:31], v[144:147], v[204:207], v[28:31]
	v_mfma_f32_16x16x32_bf16 v[24:27], v[152:155], v[204:207], v[24:27]
	v_mfma_f32_16x16x32_bf16 v[12:15], v[144:147], v[212:215], v[12:15]
	v_mfma_f32_16x16x32_bf16 v[8:11], v[152:155], v[212:215], v[8:11]
	s_setprio 0
	s_setprio 1
	v_mfma_f32_16x16x32_bf16 v[52:55], v[156:159], v[172:175], v[52:55]
	v_mfma_f32_16x16x32_bf16 v[48:51], v[164:167], v[172:175], v[48:51]
	v_mfma_f32_16x16x32_bf16 v[36:39], v[156:159], v[192:195], v[36:39]
	v_mfma_f32_16x16x32_bf16 v[32:35], v[164:167], v[192:195], v[32:35]
	v_mfma_f32_16x16x32_bf16 v[20:23], v[156:159], v[200:203], v[20:23]
	v_mfma_f32_16x16x32_bf16 v[16:19], v[164:167], v[200:203], v[16:19]
	v_mfma_f32_16x16x32_bf16 v[4:7], v[156:159], v[208:211], v[4:7]
	v_mfma_f32_16x16x32_bf16 v[0:3], v[164:167], v[208:211], v[0:3]
	v_mfma_f32_16x16x32_bf16 v[52:55], v[160:163], v[188:191], v[52:55]
	v_mfma_f32_16x16x32_bf16 v[48:51], v[168:171], v[188:191], v[48:51]
	v_mfma_f32_16x16x32_bf16 v[36:39], v[160:163], v[196:199], v[36:39]
	v_mfma_f32_16x16x32_bf16 v[32:35], v[168:171], v[196:199], v[32:35]
	s_setprio 2
	s_barrier
	v_mfma_f32_16x16x32_bf16 v[20:23], v[160:163], v[204:207], v[20:23]
	v_mfma_f32_16x16x32_bf16 v[16:19], v[168:171], v[204:207], v[16:19]
	v_mfma_f32_16x16x32_bf16 v[4:7], v[160:163], v[212:215], v[4:7]
	v_mfma_f32_16x16x32_bf16 v[0:3], v[168:171], v[212:215], v[0:3]
	s_setprio 0
	s_add_i32 s79, s79, 2
	s_add_u32 s24, s24, 0x100
	s_addc_u32 s25, s25, 0
	s_add_u32 s57, s57, 0x100
	s_addc_u32 s78, s78, 0
	s_cmp_gt_u32 s79, 61
	s_cbranch_scc0 .LBB0_687
	s_and_b64 vcc, exec, s[4:5]
	s_cbranch_vccz .LBB0_690
	s_barrier

.LBB0_761:
	s_add_u32 s34, s30, 0xfffc0080
	s_addc_u32 s35, s31, -1
	s_add_i32 s38, 0, 0x10000
	s_cmp_eq_u32 s79, 12
	s_cselect_b32 s49, s27, s35
	s_cselect_b32 s48, s26, s34
	v_add_u32_e32 v142, s38, v144
	s_cselect_b32 s35, s29, s78
	s_cselect_b32 s34, s28, s55
	s_add_i32 s39, 0, 0x14000
	ds_read_b128 v[138:141], v142
	ds_read_b128 v[146:149], v142 offset:1024
	ds_read_b128 v[150:153], v142 offset:2048
	ds_read_b128 v[154:157], v142 offset:3072
	v_add_u32_e32 v142, s39, v144
	ds_read_b128 v[158:161], v142
	ds_read_b128 v[162:165], v142 offset:1024
	ds_read_b128 v[166:169], v142 offset:2048
	ds_read_b128 v[170:173], v142 offset:3072
	s_add_u32 s98, s30, 0xfffc0000
	s_addc_u32 s99, s31, -1
	s_mov_b32 m0, s93
	s_nop 0
	global_load_lds_dwordx4 v128, s[98:99]
	s_mov_b32 m0, s85
	s_nop 0
	global_load_lds_dwordx4 v130, s[98:99]
	s_add_i32 m0, s10, 0xc000
	ds_read_b128 v[178:181], v145
	ds_read_b128 v[182:185], v145 offset:1024
	ds_read_b128 v[188:191], v145 offset:2048
	ds_read_b128 v[192:195], v145 offset:3072
	ds_read_b128 v[196:199], v145 offset:4096
	ds_read_b128 v[200:203], v145 offset:5120
	ds_read_b128 v[204:207], v145 offset:6144
	ds_read_b128 v[208:211], v145 offset:7168
	global_load_lds_dwordx4 v134, s[30:31]
	s_add_i32 m0, s10, 0xe000
	s_nop 0
	global_load_lds_dwordx4 v136, s[30:31]
	s_waitcnt vmcnt(8)
	s_waitcnt lgkmcnt(0)
	s_barrier
	s_setprio 1
	s_waitcnt lgkmcnt(0)
	v_mfma_f32_16x16x32_bf16 v[124:127], v[138:141], v[178:181], v[124:127]
	v_mfma_f32_16x16x32_bf16 v[112:115], v[150:153], v[178:181], v[112:115]
	v_mfma_f32_16x16x32_bf16 v[108:111], v[138:141], v[188:191], v[108:111]
	v_mfma_f32_16x16x32_bf16 v[96:99], v[150:153], v[188:191], v[96:99]
	v_mfma_f32_16x16x32_bf16 v[92:95], v[138:141], v[196:199], v[92:95]
	v_mfma_f32_16x16x32_bf16 v[80:83], v[150:153], v[196:199], v[80:83]
	v_mfma_f32_16x16x32_bf16 v[76:79], v[138:141], v[204:207], v[76:79]
	v_mfma_f32_16x16x32_bf16 v[64:67], v[150:153], v[204:207], v[64:67]
	v_mfma_f32_16x16x32_bf16 v[124:127], v[146:149], v[182:185], v[124:127]
	v_mfma_f32_16x16x32_bf16 v[112:115], v[154:157], v[182:185], v[112:115]
	v_mfma_f32_16x16x32_bf16 v[108:111], v[146:149], v[192:195], v[108:111]
	v_mfma_f32_16x16x32_bf16 v[96:99], v[154:157], v[192:195], v[96:99]
	v_mfma_f32_16x16x32_bf16 v[92:95], v[146:149], v[200:203], v[92:95]
	v_mfma_f32_16x16x32_bf16 v[80:83], v[154:157], v[200:203], v[80:83]
	v_mfma_f32_16x16x32_bf16 v[76:79], v[146:149], v[208:211], v[76:79]
	v_mfma_f32_16x16x32_bf16 v[64:67], v[154:157], v[208:211], v[64:67]
	s_setprio 0
	s_setprio 1
	v_mfma_f32_16x16x32_bf16 v[120:123], v[158:161], v[178:181], v[120:123]
	v_mfma_f32_16x16x32_bf16 v[116:119], v[166:169], v[178:181], v[116:119]
	v_mfma_f32_16x16x32_bf16 v[104:107], v[158:161], v[188:191], v[104:107]
	v_mfma_f32_16x16x32_bf16 v[100:103], v[166:169], v[188:191], v[100:103]
	v_mfma_f32_16x16x32_bf16 v[88:91], v[158:161], v[196:199], v[88:91]
	v_mfma_f32_16x16x32_bf16 v[84:87], v[166:169], v[196:199], v[84:87]
	v_mfma_f32_16x16x32_bf16 v[72:75], v[158:161], v[204:207], v[72:75]
	v_mfma_f32_16x16x32_bf16 v[68:71], v[166:169], v[204:207], v[68:71]
	v_mfma_f32_16x16x32_bf16 v[120:123], v[162:165], v[182:185], v[120:123]
	v_mfma_f32_16x16x32_bf16 v[116:119], v[170:173], v[182:185], v[116:119]
	v_mfma_f32_16x16x32_bf16 v[104:107], v[162:165], v[192:195], v[104:107]
	v_mfma_f32_16x16x32_bf16 v[100:103], v[170:173], v[192:195], v[100:103]
	s_setprio 2
	s_barrier
	v_mfma_f32_16x16x32_bf16 v[88:91], v[162:165], v[200:203], v[88:91]
	v_mfma_f32_16x16x32_bf16 v[84:87], v[170:173], v[200:203], v[84:87]
	v_mfma_f32_16x16x32_bf16 v[72:75], v[162:165], v[208:211], v[72:75]
	v_mfma_f32_16x16x32_bf16 v[68:71], v[170:173], v[208:211], v[68:71]
	s_setprio 0
	s_add_i32 s38, s38, s44
	s_add_u32 s90, s34, 0x80
	s_addc_u32 s91, s35, 0
	s_mov_b32 m0, s38
	ds_read_b128 v[178:181], v145 offset:16384
	ds_read_b128 v[182:185], v145 offset:17408
	ds_read_b128 v[188:191], v145 offset:18432
	ds_read_b128 v[192:195], v145 offset:19456
	ds_read_b128 v[196:199], v145 offset:20480
	ds_read_b128 v[200:203], v145 offset:21504
	ds_read_b128 v[204:207], v145 offset:22528
	ds_read_b128 v[208:211], v145 offset:23552
	global_load_lds_dwordx4 v176, s[34:35]
	s_add_i32 m0, s38, 0x2000
	s_add_u32 s80, s34, 0x40000
	s_addc_u32 s81, s35, 0
	s_add_i32 s38, s39, s44
	global_load_lds_dwordx4 v132, s[34:35]
	s_mov_b32 m0, s38
	s_nop 0
	global_load_lds_dwordx4 v176, s[80:81]
	s_add_i32 m0, s38, 0x2000
	s_nop 0
	global_load_lds_dwordx4 v132, s[80:81]
	s_waitcnt vmcnt(6)
	s_waitcnt lgkmcnt(0)
	s_barrier
	s_setprio 1
	s_waitcnt lgkmcnt(0)
	v_mfma_f32_16x16x32_bf16 v[60:63], v[138:141], v[178:181], v[60:63]
	v_mfma_f32_16x16x32_bf16 v[48:51], v[150:153], v[178:181], v[48:51]
	v_mfma_f32_16x16x32_bf16 v[44:47], v[138:141], v[188:191], v[44:47]
	v_mfma_f32_16x16x32_bf16 v[32:35], v[150:153], v[188:191], v[32:35]
	v_mfma_f32_16x16x32_bf16 v[28:31], v[138:141], v[196:199], v[28:31]
	v_mfma_f32_16x16x32_bf16 v[16:19], v[150:153], v[196:199], v[16:19]
	v_mfma_f32_16x16x32_bf16 v[12:15], v[138:141], v[204:207], v[12:15]
	v_mfma_f32_16x16x32_bf16 v[8:11], v[150:153], v[204:207], v[8:11]
	v_mfma_f32_16x16x32_bf16 v[60:63], v[146:149], v[182:185], v[60:63]
	v_mfma_f32_16x16x32_bf16 v[48:51], v[154:157], v[182:185], v[48:51]
	v_mfma_f32_16x16x32_bf16 v[44:47], v[146:149], v[192:195], v[44:47]
	v_mfma_f32_16x16x32_bf16 v[32:35], v[154:157], v[192:195], v[32:35]
	v_mfma_f32_16x16x32_bf16 v[28:31], v[146:149], v[200:203], v[28:31]
	v_mfma_f32_16x16x32_bf16 v[16:19], v[154:157], v[200:203], v[16:19]
	v_mfma_f32_16x16x32_bf16 v[12:15], v[146:149], v[208:211], v[12:15]
	v_mfma_f32_16x16x32_bf16 v[8:11], v[154:157], v[208:211], v[8:11]
	s_setprio 0
	s_setprio 1
	v_mfma_f32_16x16x32_bf16 v[56:59], v[158:161], v[178:181], v[56:59]
	v_mfma_f32_16x16x32_bf16 v[52:55], v[166:169], v[178:181], v[52:55]
	v_mfma_f32_16x16x32_bf16 v[40:43], v[158:161], v[188:191], v[40:43]
	v_mfma_f32_16x16x32_bf16 v[36:39], v[166:169], v[188:191], v[36:39]
	v_mfma_f32_16x16x32_bf16 v[24:27], v[158:161], v[196:199], v[24:27]
	v_mfma_f32_16x16x32_bf16 v[20:23], v[166:169], v[196:199], v[20:23]
	v_mfma_f32_16x16x32_bf16 v[4:7], v[158:161], v[204:207], v[4:7]
	v_mfma_f32_16x16x32_bf16 v[0:3], v[166:169], v[204:207], v[0:3]
	v_mfma_f32_16x16x32_bf16 v[56:59], v[162:165], v[182:185], v[56:59]
	v_mfma_f32_16x16x32_bf16 v[52:55], v[170:173], v[182:185], v[52:55]
	v_mfma_f32_16x16x32_bf16 v[40:43], v[162:165], v[192:195], v[40:43]
	v_mfma_f32_16x16x32_bf16 v[36:39], v[170:173], v[192:195], v[36:39]
	s_setprio 2
	s_barrier
	v_mfma_f32_16x16x32_bf16 v[24:27], v[162:165], v[200:203], v[24:27]
	v_mfma_f32_16x16x32_bf16 v[20:23], v[170:173], v[200:203], v[20:23]
	v_mfma_f32_16x16x32_bf16 v[4:7], v[162:165], v[208:211], v[4:7]
	v_mfma_f32_16x16x32_bf16 v[0:3], v[170:173], v[208:211], v[0:3]
	s_setprio 0
	s_add_i32 s38, 0, 0x18000
	s_add_i32 s39, 0, 0x1c000
	v_add_u32_e32 v154, s38, v144
	v_add_u32_e32 v170, s39, v144
	ds_read_b128 v[138:141], v154
	ds_read_b128 v[146:149], v154 offset:1024
	ds_read_b128 v[150:153], v154 offset:2048
	ds_read_b128 v[154:157], v154 offset:3072
	ds_read_b128 v[158:161], v170
	ds_read_b128 v[162:165], v170 offset:1024
	ds_read_b128 v[166:169], v170 offset:2048
	ds_read_b128 v[170:173], v170 offset:3072
	s_mov_b32 m0, s10
	s_nop 0
	global_load_lds_dwordx4 v128, s[48:49]
	s_mov_b32 m0, s11
	s_nop 0
	global_load_lds_dwordx4 v130, s[48:49]
	s_add_u32 s48, s48, 0x40000
	s_addc_u32 s49, s49, 0
	s_mov_b32 m0, s8
	ds_read_b128 v[178:181], v145 offset:32768
	ds_read_b128 v[182:185], v145 offset:33792
	ds_read_b128 v[188:191], v145 offset:34816
	ds_read_b128 v[192:195], v145 offset:35840
	ds_read_b128 v[196:199], v145 offset:36864
	ds_read_b128 v[200:203], v145 offset:37888
	ds_read_b128 v[204:207], v145 offset:38912
	ds_read_b128 v[208:211], v145 offset:39936
	global_load_lds_dwordx4 v128, s[48:49]
	s_mov_b32 m0, s9
	s_nop 0
	global_load_lds_dwordx4 v130, s[48:49]
	s_waitcnt vmcnt(8)
	s_waitcnt lgkmcnt(0)
	s_barrier
	s_setprio 1
	s_waitcnt lgkmcnt(0)
	v_mfma_f32_16x16x32_bf16 v[124:127], v[138:141], v[178:181], v[124:127]
	v_mfma_f32_16x16x32_bf16 v[112:115], v[150:153], v[178:181], v[112:115]
	v_mfma_f32_16x16x32_bf16 v[108:111], v[138:141], v[188:191], v[108:111]
	v_mfma_f32_16x16x32_bf16 v[96:99], v[150:153], v[188:191], v[96:99]
	v_mfma_f32_16x16x32_bf16 v[92:95], v[138:141], v[196:199], v[92:95]
	v_mfma_f32_16x16x32_bf16 v[80:83], v[150:153], v[196:199], v[80:83]
	v_mfma_f32_16x16x32_bf16 v[76:79], v[138:141], v[204:207], v[76:79]
	v_mfma_f32_16x16x32_bf16 v[64:67], v[150:153], v[204:207], v[64:67]
	v_mfma_f32_16x16x32_bf16 v[124:127], v[146:149], v[182:185], v[124:127]
	v_mfma_f32_16x16x32_bf16 v[112:115], v[154:157], v[182:185], v[112:115]
	v_mfma_f32_16x16x32_bf16 v[108:111], v[146:149], v[192:195], v[108:111]
	v_mfma_f32_16x16x32_bf16 v[96:99], v[154:157], v[192:195], v[96:99]
	v_mfma_f32_16x16x32_bf16 v[92:95], v[146:149], v[200:203], v[92:95]
	v_mfma_f32_16x16x32_bf16 v[80:83], v[154:157], v[200:203], v[80:83]
	v_mfma_f32_16x16x32_bf16 v[76:79], v[146:149], v[208:211], v[76:79]
	v_mfma_f32_16x16x32_bf16 v[64:67], v[154:157], v[208:211], v[64:67]
	s_setprio 0
	s_setprio 1
	v_mfma_f32_16x16x32_bf16 v[120:123], v[158:161], v[178:181], v[120:123]
	v_mfma_f32_16x16x32_bf16 v[116:119], v[166:169], v[178:181], v[116:119]
	v_mfma_f32_16x16x32_bf16 v[104:107], v[158:161], v[188:191], v[104:107]
	v_mfma_f32_16x16x32_bf16 v[100:103], v[166:169], v[188:191], v[100:103]
	v_mfma_f32_16x16x32_bf16 v[88:91], v[158:161], v[196:199], v[88:91]
	v_mfma_f32_16x16x32_bf16 v[84:87], v[166:169], v[196:199], v[84:87]
	v_mfma_f32_16x16x32_bf16 v[72:75], v[158:161], v[204:207], v[72:75]
	v_mfma_f32_16x16x32_bf16 v[68:71], v[166:169], v[204:207], v[68:71]
	v_mfma_f32_16x16x32_bf16 v[120:123], v[162:165], v[182:185], v[120:123]
	v_mfma_f32_16x16x32_bf16 v[116:119], v[170:173], v[182:185], v[116:119]
	v_mfma_f32_16x16x32_bf16 v[104:107], v[162:165], v[192:195], v[104:107]
	v_mfma_f32_16x16x32_bf16 v[100:103], v[170:173], v[192:195], v[100:103]
	s_setprio 2
	s_barrier
	v_mfma_f32_16x16x32_bf16 v[88:91], v[162:165], v[200:203], v[88:91]
	v_mfma_f32_16x16x32_bf16 v[84:87], v[170:173], v[200:203], v[84:87]
	v_mfma_f32_16x16x32_bf16 v[72:75], v[162:165], v[208:211], v[72:75]
	v_mfma_f32_16x16x32_bf16 v[68:71], v[170:173], v[208:211], v[68:71]
	s_setprio 0
	s_add_i32 s38, s38, s44
	s_mov_b32 m0, s38
	ds_read_b128 v[178:181], v145 offset:49152
	ds_read_b128 v[182:185], v145 offset:50176
	ds_read_b128 v[188:191], v145 offset:51200
	ds_read_b128 v[192:195], v145 offset:52224
	ds_read_b128 v[196:199], v145 offset:53248
	ds_read_b128 v[200:203], v145 offset:54272
	ds_read_b128 v[204:207], v145 offset:55296
	ds_read_b128 v[208:211], v145 offset:56320
	global_load_lds_dwordx4 v176, s[90:91]
	s_add_i32 m0, s38, 0x2000
	s_add_u32 s34, s34, 0x40080
	s_addc_u32 s35, s35, 0
	s_add_i32 s38, s39, s44
	global_load_lds_dwordx4 v132, s[90:91]
	s_mov_b32 m0, s38
	s_nop 0
	global_load_lds_dwordx4 v176, s[34:35]
	s_add_i32 m0, s38, 0x2000
	s_nop 0
	global_load_lds_dwordx4 v132, s[34:35]
	s_waitcnt vmcnt(6)
	s_waitcnt lgkmcnt(0)
	s_barrier
	s_setprio 1
	s_waitcnt lgkmcnt(0)
	v_mfma_f32_16x16x32_bf16 v[60:63], v[138:141], v[178:181], v[60:63]
	v_mfma_f32_16x16x32_bf16 v[48:51], v[150:153], v[178:181], v[48:51]
	v_mfma_f32_16x16x32_bf16 v[44:47], v[138:141], v[188:191], v[44:47]
	v_mfma_f32_16x16x32_bf16 v[32:35], v[150:153], v[188:191], v[32:35]
	v_mfma_f32_16x16x32_bf16 v[28:31], v[138:141], v[196:199], v[28:31]
	v_mfma_f32_16x16x32_bf16 v[16:19], v[150:153], v[196:199], v[16:19]
	v_mfma_f32_16x16x32_bf16 v[12:15], v[138:141], v[204:207], v[12:15]
	v_mfma_f32_16x16x32_bf16 v[8:11], v[150:153], v[204:207], v[8:11]
	v_mfma_f32_16x16x32_bf16 v[60:63], v[146:149], v[182:185], v[60:63]
	v_mfma_f32_16x16x32_bf16 v[48:51], v[154:157], v[182:185], v[48:51]
	v_mfma_f32_16x16x32_bf16 v[44:47], v[146:149], v[192:195], v[44:47]
	v_mfma_f32_16x16x32_bf16 v[32:35], v[154:157], v[192:195], v[32:35]
	v_mfma_f32_16x16x32_bf16 v[28:31], v[146:149], v[200:203], v[28:31]
	v_mfma_f32_16x16x32_bf16 v[16:19], v[154:157], v[200:203], v[16:19]
	v_mfma_f32_16x16x32_bf16 v[12:15], v[146:149], v[208:211], v[12:15]
	v_mfma_f32_16x16x32_bf16 v[8:11], v[154:157], v[208:211], v[8:11]
	s_setprio 0
	s_setprio 1
	v_mfma_f32_16x16x32_bf16 v[56:59], v[158:161], v[178:181], v[56:59]
	v_mfma_f32_16x16x32_bf16 v[52:55], v[166:169], v[178:181], v[52:55]
	v_mfma_f32_16x16x32_bf16 v[40:43], v[158:161], v[188:191], v[40:43]
	v_mfma_f32_16x16x32_bf16 v[36:39], v[166:169], v[188:191], v[36:39]
	v_mfma_f32_16x16x32_bf16 v[24:27], v[158:161], v[196:199], v[24:27]
	v_mfma_f32_16x16x32_bf16 v[20:23], v[166:169], v[196:199], v[20:23]
	v_mfma_f32_16x16x32_bf16 v[4:7], v[158:161], v[204:207], v[4:7]
	v_mfma_f32_16x16x32_bf16 v[0:3], v[166:169], v[204:207], v[0:3]
	v_mfma_f32_16x16x32_bf16 v[56:59], v[162:165], v[182:185], v[56:59]
	v_mfma_f32_16x16x32_bf16 v[52:55], v[170:173], v[182:185], v[52:55]
	v_mfma_f32_16x16x32_bf16 v[40:43], v[162:165], v[192:195], v[40:43]
	v_mfma_f32_16x16x32_bf16 v[36:39], v[170:173], v[192:195], v[36:39]
	s_setprio 2
	s_barrier
	v_mfma_f32_16x16x32_bf16 v[24:27], v[162:165], v[200:203], v[24:27]
	v_mfma_f32_16x16x32_bf16 v[20:23], v[170:173], v[200:203], v[20:23]
	v_mfma_f32_16x16x32_bf16 v[4:7], v[162:165], v[208:211], v[4:7]
	v_mfma_f32_16x16x32_bf16 v[0:3], v[170:173], v[208:211], v[0:3]
	s_setprio 0
	s_add_i32 s79, s79, 2
	s_add_u32 s30, s30, 0x100
	s_addc_u32 s31, s31, 0
	s_add_u32 s55, s55, 0x100
	s_addc_u32 s78, s78, 0
	s_cmp_gt_u32 s79, 13
	s_cbranch_scc0 .LBB0_761
	s_and_b64 vcc, exec, s[18:19]
	s_cbranch_vccz .LBB0_764
	s_barrier

.LBB0_921:
	s_add_u32 s24, s22, 0xfff00080
	s_addc_u32 s25, s23, -1
	s_add_i32 s38, 0, 0x10000
	s_cmp_eq_u32 s79, 60
	s_cselect_b32 s27, s19, s25
	s_cselect_b32 s26, s18, s24
	s_cselect_b32 s25, s21, s78
	s_cselect_b32 s24, s20, s55
	s_add_i32 s39, 0, 0x14000
	v_add_u32_e32 v140, s38, v160
	v_add_u32_e32 v158, s39, v160
	ds_read_b128 v[120:123], v140
	ds_read_b128 v[132:135], v140 offset:1024
	ds_read_b128 v[136:139], v140 offset:2048
	ds_read_b128 v[140:143], v140 offset:3072
	ds_read_b128 v[154:157], v158
	ds_read_b128 v[162:165], v158 offset:1024
	ds_read_b128 v[166:169], v158 offset:2048
	ds_read_b128 v[170:173], v158 offset:3072
	s_add_u32 s96, s22, 0xfff00000
	s_addc_u32 s97, s23, -1
	s_mov_b32 m0, s49
	s_nop 0
	global_load_lds_dwordx4 v144, s[96:97]
	s_mov_b32 m0, s50
	s_nop 0
	global_load_lds_dwordx4 v146, s[96:97]
	s_add_i32 m0, s34, 0xc000
	ds_read_b128 v[178:181], v161
	ds_read_b128 v[182:185], v161 offset:1024
	ds_read_b128 v[188:191], v161 offset:2048
	ds_read_b128 v[192:195], v161 offset:3072
	ds_read_b128 v[196:199], v161 offset:4096
	ds_read_b128 v[200:203], v161 offset:5120
	ds_read_b128 v[204:207], v161 offset:6144
	ds_read_b128 v[208:211], v161 offset:7168
	global_load_lds_dwordx4 v150, s[22:23]
	s_add_i32 m0, s34, 0xe000
	s_nop 0
	global_load_lds_dwordx4 v152, s[22:23]
	s_waitcnt vmcnt(8)
	s_waitcnt lgkmcnt(0)
	s_barrier
	s_setprio 1
	s_waitcnt lgkmcnt(0)
	v_mfma_f32_16x16x32_bf16 v[128:131], v[120:123], v[178:181], v[128:131]
	v_mfma_f32_16x16x32_bf16 v[124:127], v[136:139], v[178:181], v[124:127]
	v_mfma_f32_16x16x32_bf16 v[108:111], v[120:123], v[188:191], v[108:111]
	v_mfma_f32_16x16x32_bf16 v[104:107], v[136:139], v[188:191], v[104:107]
	v_mfma_f32_16x16x32_bf16 v[92:95], v[120:123], v[196:199], v[92:95]
	v_mfma_f32_16x16x32_bf16 v[88:91], v[136:139], v[196:199], v[88:91]
	v_mfma_f32_16x16x32_bf16 v[76:79], v[120:123], v[204:207], v[76:79]
	v_mfma_f32_16x16x32_bf16 v[72:75], v[136:139], v[204:207], v[72:75]
	v_mfma_f32_16x16x32_bf16 v[128:131], v[132:135], v[182:185], v[128:131]
	v_mfma_f32_16x16x32_bf16 v[124:127], v[140:143], v[182:185], v[124:127]
	v_mfma_f32_16x16x32_bf16 v[108:111], v[132:135], v[192:195], v[108:111]
	v_mfma_f32_16x16x32_bf16 v[104:107], v[140:143], v[192:195], v[104:107]
	v_mfma_f32_16x16x32_bf16 v[92:95], v[132:135], v[200:203], v[92:95]
	v_mfma_f32_16x16x32_bf16 v[88:91], v[140:143], v[200:203], v[88:91]
	v_mfma_f32_16x16x32_bf16 v[76:79], v[132:135], v[208:211], v[76:79]
	v_mfma_f32_16x16x32_bf16 v[72:75], v[140:143], v[208:211], v[72:75]
	s_setprio 0
	s_setprio 1
	v_mfma_f32_16x16x32_bf16 v[116:119], v[154:157], v[178:181], v[116:119]
	v_mfma_f32_16x16x32_bf16 v[112:115], v[166:169], v[178:181], v[112:115]
	v_mfma_f32_16x16x32_bf16 v[100:103], v[154:157], v[188:191], v[100:103]
	v_mfma_f32_16x16x32_bf16 v[96:99], v[166:169], v[188:191], v[96:99]
	v_mfma_f32_16x16x32_bf16 v[84:87], v[154:157], v[196:199], v[84:87]
	v_mfma_f32_16x16x32_bf16 v[80:83], v[166:169], v[196:199], v[80:83]
	v_mfma_f32_16x16x32_bf16 v[68:71], v[154:157], v[204:207], v[68:71]
	v_mfma_f32_16x16x32_bf16 v[64:67], v[166:169], v[204:207], v[64:67]
	v_mfma_f32_16x16x32_bf16 v[116:119], v[162:165], v[182:185], v[116:119]
	v_mfma_f32_16x16x32_bf16 v[112:115], v[170:173], v[182:185], v[112:115]
	v_mfma_f32_16x16x32_bf16 v[100:103], v[162:165], v[192:195], v[100:103]
	v_mfma_f32_16x16x32_bf16 v[96:99], v[170:173], v[192:195], v[96:99]
	s_setprio 2
	s_barrier
	v_mfma_f32_16x16x32_bf16 v[84:87], v[162:165], v[200:203], v[84:87]
	v_mfma_f32_16x16x32_bf16 v[80:83], v[170:173], v[200:203], v[80:83]
	v_mfma_f32_16x16x32_bf16 v[68:71], v[162:165], v[208:211], v[68:71]
	v_mfma_f32_16x16x32_bf16 v[64:67], v[170:173], v[208:211], v[64:67]
	s_setprio 0
	s_add_i32 s38, s38, s31
	s_add_u32 s90, s24, 0x80
	s_addc_u32 s91, s25, 0
	s_mov_b32 m0, s38
	ds_read_b128 v[178:181], v161 offset:16384
	ds_read_b128 v[182:185], v161 offset:17408
	ds_read_b128 v[188:191], v161 offset:18432
	ds_read_b128 v[192:195], v161 offset:19456
	ds_read_b128 v[196:199], v161 offset:20480
	ds_read_b128 v[200:203], v161 offset:21504
	ds_read_b128 v[204:207], v161 offset:22528
	ds_read_b128 v[208:211], v161 offset:23552
	global_load_lds_dwordx4 v176, s[24:25]
	s_add_i32 m0, s38, 0x2000
	s_add_u32 s80, s24, 0x100000
	s_addc_u32 s81, s25, 0
	s_add_i32 s38, s39, s31
	global_load_lds_dwordx4 v148, s[24:25]
	s_mov_b32 m0, s38
	s_nop 0
	global_load_lds_dwordx4 v176, s[80:81]
	s_add_i32 m0, s38, 0x2000
	s_nop 0
	global_load_lds_dwordx4 v148, s[80:81]
	s_waitcnt vmcnt(6)
	s_waitcnt lgkmcnt(0)
	s_barrier
	s_setprio 1
	s_waitcnt lgkmcnt(0)
	v_mfma_f32_16x16x32_bf16 v[60:63], v[120:123], v[178:181], v[60:63]
	v_mfma_f32_16x16x32_bf16 v[56:59], v[136:139], v[178:181], v[56:59]
	v_mfma_f32_16x16x32_bf16 v[48:51], v[120:123], v[188:191], v[48:51]
	v_mfma_f32_16x16x32_bf16 v[40:43], v[136:139], v[188:191], v[40:43]
	v_mfma_f32_16x16x32_bf16 v[32:35], v[120:123], v[196:199], v[32:35]
	v_mfma_f32_16x16x32_bf16 v[24:27], v[136:139], v[196:199], v[24:27]
	v_mfma_f32_16x16x32_bf16 v[16:19], v[120:123], v[204:207], v[16:19]
	v_mfma_f32_16x16x32_bf16 v[8:11], v[136:139], v[204:207], v[8:11]
	v_mfma_f32_16x16x32_bf16 v[60:63], v[132:135], v[182:185], v[60:63]
	v_mfma_f32_16x16x32_bf16 v[56:59], v[140:143], v[182:185], v[56:59]
	v_mfma_f32_16x16x32_bf16 v[48:51], v[132:135], v[192:195], v[48:51]
	v_mfma_f32_16x16x32_bf16 v[40:43], v[140:143], v[192:195], v[40:43]
	v_mfma_f32_16x16x32_bf16 v[32:35], v[132:135], v[200:203], v[32:35]
	v_mfma_f32_16x16x32_bf16 v[24:27], v[140:143], v[200:203], v[24:27]
	v_mfma_f32_16x16x32_bf16 v[16:19], v[132:135], v[208:211], v[16:19]
	v_mfma_f32_16x16x32_bf16 v[8:11], v[140:143], v[208:211], v[8:11]
	s_setprio 0
	s_setprio 1
	v_mfma_f32_16x16x32_bf16 v[52:55], v[154:157], v[178:181], v[52:55]
	v_mfma_f32_16x16x32_bf16 v[44:47], v[166:169], v[178:181], v[44:47]
	v_mfma_f32_16x16x32_bf16 v[36:39], v[154:157], v[188:191], v[36:39]
	v_mfma_f32_16x16x32_bf16 v[28:31], v[166:169], v[188:191], v[28:31]
	v_mfma_f32_16x16x32_bf16 v[20:23], v[154:157], v[196:199], v[20:23]
	v_mfma_f32_16x16x32_bf16 v[12:15], v[166:169], v[196:199], v[12:15]
	v_mfma_f32_16x16x32_bf16 v[4:7], v[154:157], v[204:207], v[4:7]
	v_mfma_f32_16x16x32_bf16 v[0:3], v[166:169], v[204:207], v[0:3]
	v_mfma_f32_16x16x32_bf16 v[52:55], v[162:165], v[182:185], v[52:55]
	v_mfma_f32_16x16x32_bf16 v[44:47], v[170:173], v[182:185], v[44:47]
	v_mfma_f32_16x16x32_bf16 v[36:39], v[162:165], v[192:195], v[36:39]
	v_mfma_f32_16x16x32_bf16 v[28:31], v[170:173], v[192:195], v[28:31]
	s_setprio 2
	s_barrier
	v_mfma_f32_16x16x32_bf16 v[20:23], v[162:165], v[200:203], v[20:23]
	v_mfma_f32_16x16x32_bf16 v[12:15], v[170:173], v[200:203], v[12:15]
	v_mfma_f32_16x16x32_bf16 v[4:7], v[162:165], v[208:211], v[4:7]
	v_mfma_f32_16x16x32_bf16 v[0:3], v[170:173], v[208:211], v[0:3]
	s_setprio 0
	s_add_i32 s38, 0, 0x18000
	s_add_i32 s39, 0, 0x1c000
	v_add_u32_e32 v140, s38, v160
	v_add_u32_e32 v170, s39, v160
	ds_read_b128 v[120:123], v140
	ds_read_b128 v[132:135], v140 offset:1024
	ds_read_b128 v[136:139], v140 offset:2048
	ds_read_b128 v[140:143], v140 offset:3072
	ds_read_b128 v[154:157], v170
	ds_read_b128 v[162:165], v170 offset:1024
	ds_read_b128 v[166:169], v170 offset:2048
	ds_read_b128 v[170:173], v170 offset:3072
	s_mov_b32 m0, s34
	s_nop 0
	global_load_lds_dwordx4 v144, s[26:27]
	s_mov_b32 m0, s35
	s_nop 0
	global_load_lds_dwordx4 v146, s[26:27]
	s_add_u32 s26, s26, 0x100000
	s_addc_u32 s27, s27, 0
	s_mov_b32 m0, s36
	ds_read_b128 v[178:181], v161 offset:32768
	ds_read_b128 v[182:185], v161 offset:33792
	ds_read_b128 v[188:191], v161 offset:34816
	ds_read_b128 v[192:195], v161 offset:35840
	ds_read_b128 v[196:199], v161 offset:36864
	ds_read_b128 v[200:203], v161 offset:37888
	ds_read_b128 v[204:207], v161 offset:38912
	ds_read_b128 v[208:211], v161 offset:39936
	global_load_lds_dwordx4 v144, s[26:27]
	s_mov_b32 m0, s43
	s_nop 0
	global_load_lds_dwordx4 v146, s[26:27]
	s_waitcnt vmcnt(8)
	s_waitcnt lgkmcnt(0)
	s_barrier
	s_setprio 1
	s_waitcnt lgkmcnt(0)
	v_mfma_f32_16x16x32_bf16 v[128:131], v[120:123], v[178:181], v[128:131]
	v_mfma_f32_16x16x32_bf16 v[124:127], v[136:139], v[178:181], v[124:127]
	v_mfma_f32_16x16x32_bf16 v[108:111], v[120:123], v[188:191], v[108:111]
	v_mfma_f32_16x16x32_bf16 v[104:107], v[136:139], v[188:191], v[104:107]
	v_mfma_f32_16x16x32_bf16 v[92:95], v[120:123], v[196:199], v[92:95]
	v_mfma_f32_16x16x32_bf16 v[88:91], v[136:139], v[196:199], v[88:91]
	v_mfma_f32_16x16x32_bf16 v[76:79], v[120:123], v[204:207], v[76:79]
	v_mfma_f32_16x16x32_bf16 v[72:75], v[136:139], v[204:207], v[72:75]
	v_mfma_f32_16x16x32_bf16 v[128:131], v[132:135], v[182:185], v[128:131]
	v_mfma_f32_16x16x32_bf16 v[124:127], v[140:143], v[182:185], v[124:127]
	v_mfma_f32_16x16x32_bf16 v[108:111], v[132:135], v[192:195], v[108:111]
	v_mfma_f32_16x16x32_bf16 v[104:107], v[140:143], v[192:195], v[104:107]
	v_mfma_f32_16x16x32_bf16 v[92:95], v[132:135], v[200:203], v[92:95]
	v_mfma_f32_16x16x32_bf16 v[88:91], v[140:143], v[200:203], v[88:91]
	v_mfma_f32_16x16x32_bf16 v[76:79], v[132:135], v[208:211], v[76:79]
	v_mfma_f32_16x16x32_bf16 v[72:75], v[140:143], v[208:211], v[72:75]
	s_setprio 0
	s_setprio 1
	v_mfma_f32_16x16x32_bf16 v[116:119], v[154:157], v[178:181], v[116:119]
	v_mfma_f32_16x16x32_bf16 v[112:115], v[166:169], v[178:181], v[112:115]
	v_mfma_f32_16x16x32_bf16 v[100:103], v[154:157], v[188:191], v[100:103]
	v_mfma_f32_16x16x32_bf16 v[96:99], v[166:169], v[188:191], v[96:99]
	v_mfma_f32_16x16x32_bf16 v[84:87], v[154:157], v[196:199], v[84:87]
	v_mfma_f32_16x16x32_bf16 v[80:83], v[166:169], v[196:199], v[80:83]
	v_mfma_f32_16x16x32_bf16 v[68:71], v[154:157], v[204:207], v[68:71]
	v_mfma_f32_16x16x32_bf16 v[64:67], v[166:169], v[204:207], v[64:67]
	v_mfma_f32_16x16x32_bf16 v[116:119], v[162:165], v[182:185], v[116:119]
	v_mfma_f32_16x16x32_bf16 v[112:115], v[170:173], v[182:185], v[112:115]
	v_mfma_f32_16x16x32_bf16 v[100:103], v[162:165], v[192:195], v[100:103]
	v_mfma_f32_16x16x32_bf16 v[96:99], v[170:173], v[192:195], v[96:99]
	s_setprio 2
	s_barrier
	v_mfma_f32_16x16x32_bf16 v[84:87], v[162:165], v[200:203], v[84:87]
	v_mfma_f32_16x16x32_bf16 v[80:83], v[170:173], v[200:203], v[80:83]
	v_mfma_f32_16x16x32_bf16 v[68:71], v[162:165], v[208:211], v[68:71]
	v_mfma_f32_16x16x32_bf16 v[64:67], v[170:173], v[208:211], v[64:67]
	s_setprio 0
	s_add_i32 s26, s38, s31
	s_mov_b32 m0, s26
	ds_read_b128 v[178:181], v161 offset:49152
	ds_read_b128 v[182:185], v161 offset:50176
	ds_read_b128 v[188:191], v161 offset:51200
	ds_read_b128 v[192:195], v161 offset:52224
	ds_read_b128 v[196:199], v161 offset:53248
	ds_read_b128 v[200:203], v161 offset:54272
	ds_read_b128 v[204:207], v161 offset:55296
	ds_read_b128 v[208:211], v161 offset:56320
	global_load_lds_dwordx4 v176, s[90:91]
	s_add_i32 m0, s26, 0x2000
	s_add_u32 s24, s24, 0x100080
	s_addc_u32 s25, s25, 0
	s_add_i32 s26, s39, s31
	global_load_lds_dwordx4 v148, s[90:91]
	s_mov_b32 m0, s26
	s_nop 0
	global_load_lds_dwordx4 v176, s[24:25]
	s_add_i32 m0, s26, 0x2000
	s_nop 0
	global_load_lds_dwordx4 v148, s[24:25]
	s_waitcnt vmcnt(6)
	s_waitcnt lgkmcnt(0)
	s_barrier
	s_setprio 1
	s_waitcnt lgkmcnt(0)
	v_mfma_f32_16x16x32_bf16 v[60:63], v[120:123], v[178:181], v[60:63]
	v_mfma_f32_16x16x32_bf16 v[56:59], v[136:139], v[178:181], v[56:59]
	v_mfma_f32_16x16x32_bf16 v[48:51], v[120:123], v[188:191], v[48:51]
	v_mfma_f32_16x16x32_bf16 v[40:43], v[136:139], v[188:191], v[40:43]
	v_mfma_f32_16x16x32_bf16 v[32:35], v[120:123], v[196:199], v[32:35]
	v_mfma_f32_16x16x32_bf16 v[24:27], v[136:139], v[196:199], v[24:27]
	v_mfma_f32_16x16x32_bf16 v[16:19], v[120:123], v[204:207], v[16:19]
	v_mfma_f32_16x16x32_bf16 v[8:11], v[136:139], v[204:207], v[8:11]
	v_mfma_f32_16x16x32_bf16 v[60:63], v[132:135], v[182:185], v[60:63]
	v_mfma_f32_16x16x32_bf16 v[56:59], v[140:143], v[182:185], v[56:59]
	v_mfma_f32_16x16x32_bf16 v[48:51], v[132:135], v[192:195], v[48:51]
	v_mfma_f32_16x16x32_bf16 v[40:43], v[140:143], v[192:195], v[40:43]
	v_mfma_f32_16x16x32_bf16 v[32:35], v[132:135], v[200:203], v[32:35]
	v_mfma_f32_16x16x32_bf16 v[24:27], v[140:143], v[200:203], v[24:27]
	v_mfma_f32_16x16x32_bf16 v[16:19], v[132:135], v[208:211], v[16:19]
	v_mfma_f32_16x16x32_bf16 v[8:11], v[140:143], v[208:211], v[8:11]
	s_setprio 0
	s_setprio 1
	v_mfma_f32_16x16x32_bf16 v[52:55], v[154:157], v[178:181], v[52:55]
	v_mfma_f32_16x16x32_bf16 v[44:47], v[166:169], v[178:181], v[44:47]
	v_mfma_f32_16x16x32_bf16 v[36:39], v[154:157], v[188:191], v[36:39]
	v_mfma_f32_16x16x32_bf16 v[28:31], v[166:169], v[188:191], v[28:31]
	v_mfma_f32_16x16x32_bf16 v[20:23], v[154:157], v[196:199], v[20:23]
	v_mfma_f32_16x16x32_bf16 v[12:15], v[166:169], v[196:199], v[12:15]
	v_mfma_f32_16x16x32_bf16 v[4:7], v[154:157], v[204:207], v[4:7]
	v_mfma_f32_16x16x32_bf16 v[0:3], v[166:169], v[204:207], v[0:3]
	v_mfma_f32_16x16x32_bf16 v[52:55], v[162:165], v[182:185], v[52:55]
	v_mfma_f32_16x16x32_bf16 v[44:47], v[170:173], v[182:185], v[44:47]
	v_mfma_f32_16x16x32_bf16 v[36:39], v[162:165], v[192:195], v[36:39]
	v_mfma_f32_16x16x32_bf16 v[28:31], v[170:173], v[192:195], v[28:31]
	s_setprio 2
	s_barrier
	v_mfma_f32_16x16x32_bf16 v[20:23], v[162:165], v[200:203], v[20:23]
	v_mfma_f32_16x16x32_bf16 v[12:15], v[170:173], v[200:203], v[12:15]
	v_mfma_f32_16x16x32_bf16 v[4:7], v[162:165], v[208:211], v[4:7]
	v_mfma_f32_16x16x32_bf16 v[0:3], v[170:173], v[208:211], v[0:3]
	s_setprio 0
	s_add_i32 s79, s79, 2
	s_add_u32 s22, s22, 0x100
	s_addc_u32 s23, s23, 0
	s_add_u32 s55, s55, 0x100
	s_addc_u32 s78, s78, 0
	s_cmp_gt_u32 s79, 61
	s_cbranch_scc0 .LBB0_921
	s_and_b64 vcc, exec, s[8:9]
	s_cbranch_vccz .LBB0_924
	s_barrier
